# attention hot loop: V/K fragment ring in dead VGPRs with counted lgkmcnt waits, plain row-sum chains instead of v_pk_add, global_load saddr instead of flat_load
# speedup vs baseline: 1.0224x; 1.0224x over previous
.LBB0_505:
	v_add_f32_e32 v16, 0, v32
	v_add_f32_e32 v16, v33, v16
	v_add_f32_e32 v17, 0, v40
	v_add_f32_e32 v16, v34, v16
	v_add_f32_e32 v17, v41, v17
	v_add_f32_e32 v16, v35, v16
	v_add_f32_e32 v17, v42, v17
	v_add_f32_e32 v16, v36, v16
	v_add_f32_e32 v17, v43, v17
	v_add_f32_e32 v16, v37, v16
	v_add_f32_e32 v17, v44, v17
	v_add_f32_e32 v16, v38, v16
	v_add_f32_e32 v17, v45, v17
	v_add_f32_e32 v16, v39, v16
	v_add_f32_e32 v17, v46, v17
	v_add_f32_e32 v16, 0, v16
	v_add_f32_e32 v17, v47, v17
	v_add_f32_e32 v18, 0, v48
	v_add_f32_e32 v16, v17, v16
	v_add_f32_e32 v17, 0, v56
	v_add_f32_e32 v18, v49, v18
	v_add_f32_e32 v17, v57, v17
	v_add_f32_e32 v18, v50, v18
	v_add_f32_e32 v17, v58, v17
	v_add_f32_e32 v18, v51, v18
	v_add_f32_e32 v17, v59, v17
	v_add_f32_e32 v18, v52, v18
	v_add_f32_e32 v17, v60, v17
	v_add_f32_e32 v18, v53, v18
	v_add_f32_e32 v17, v61, v17
	v_add_f32_e32 v18, v54, v18
	s_waitcnt vmcnt(0)
	ds_write_b64 v216, v[64:65] offset:18432
	s_waitcnt lgkmcnt(0)
	ds_write_b64 v216, v[68:69] offset:27648
	ds_write2st64_b64 v217, v[66:67], v[70:71] offset0:36 offset1:54
	ds_write_b128 v213, v[144:147]
	v_add_f32_e32 v17, v62, v17
	v_add_f32_e32 v18, v55, v18
	s_waitcnt lgkmcnt(0)
	s_barrier
	v_add_f32_e32 v17, v63, v17
	v_add_f32_e32 v16, v18, v16
	v_mov_b32_e32 v31, 0
	v_cvt_pk_bf16_f32 v160, v32, v33
	v_cvt_pk_bf16_f32 v161, v34, v35
	v_cvt_pk_bf16_f32 v162, v36, v37
	v_cvt_pk_bf16_f32 v163, v38, v39
	v_cvt_pk_bf16_f32 v148, v40, v41
	v_cvt_pk_bf16_f32 v149, v42, v43
	v_cvt_pk_bf16_f32 v150, v44, v45
	v_cvt_pk_bf16_f32 v151, v46, v47
	v_cvt_pk_bf16_f32 v152, v48, v49
	v_cvt_pk_bf16_f32 v153, v50, v51
	v_cvt_pk_bf16_f32 v154, v52, v53
	v_cvt_pk_bf16_f32 v155, v54, v55
	v_add_f32_e32 v193, v17, v16
	v_cvt_pk_bf16_f32 v156, v56, v57
	v_cvt_pk_bf16_f32 v157, v58, v59
	v_cvt_pk_bf16_f32 v158, v60, v61
	v_cvt_pk_bf16_f32 v159, v62, v63
	s_andn2_b64 vcc, exec, s[2:3]
	s_cbranch_vccnz .LBB0_512
	v_mov_b32_e32 v32, 0
	s_mov_b32 s93, 0
	s_movk_i32 s15, 0x80
	s_mov_b64 s[6:7], 0x80
	v_mov_b32_e32 v33, v32
	v_mov_b32_e32 v34, v32
	v_mov_b32_e32 v35, v32
	v_mov_b32_e32 v36, v32
	v_mov_b32_e32 v37, v32
	v_mov_b32_e32 v38, v32
	v_mov_b32_e32 v39, v32
	v_mov_b32_e32 v40, v32
	v_mov_b32_e32 v41, v32
	v_mov_b32_e32 v42, v32
	v_mov_b32_e32 v43, v32
	v_mov_b32_e32 v44, v32
	v_mov_b32_e32 v45, v32
	v_mov_b32_e32 v46, v32
	v_mov_b32_e32 v47, v32
	v_mov_b32_e32 v64, v32
	v_mov_b32_e32 v65, v32
	v_mov_b32_e32 v66, v32
	v_mov_b32_e32 v67, v32
	v_mov_b32_e32 v68, v32
	v_mov_b32_e32 v69, v32
	v_mov_b32_e32 v70, v32
	v_mov_b32_e32 v71, v32
	v_mov_b32_e32 v72, v32
	v_mov_b32_e32 v73, v32
	v_mov_b32_e32 v74, v32
	v_mov_b32_e32 v75, v32
	v_mov_b32_e32 v76, v32
	v_mov_b32_e32 v77, v32
	v_mov_b32_e32 v78, v32
	v_mov_b32_e32 v79, v32
	v_mov_b32_e32 v48, v32
	v_mov_b32_e32 v49, v32
	v_mov_b32_e32 v50, v32
	v_mov_b32_e32 v51, v32
	v_mov_b32_e32 v52, v32
	v_mov_b32_e32 v53, v32
	v_mov_b32_e32 v54, v32
	v_mov_b32_e32 v55, v32
	v_mov_b32_e32 v56, v32
	v_mov_b32_e32 v57, v32
	v_mov_b32_e32 v58, v32
	v_mov_b32_e32 v59, v32
	v_mov_b32_e32 v60, v32
	v_mov_b32_e32 v61, v32
	v_mov_b32_e32 v62, v32
	v_mov_b32_e32 v63, v32
	v_mov_b32_e32 v16, v32
	v_mov_b32_e32 v17, v32
	v_mov_b32_e32 v18, v32
	v_mov_b32_e32 v19, v32
	v_mov_b32_e32 v20, v32
	v_mov_b32_e32 v21, v32
	v_mov_b32_e32 v22, v32
	v_mov_b32_e32 v23, v32
	v_mov_b32_e32 v24, v32
	v_mov_b32_e32 v25, v32
	v_mov_b32_e32 v26, v32
	v_mov_b32_e32 v27, v32
	v_mov_b32_e32 v28, v32
	v_mov_b32_e32 v29, v32
	v_mov_b32_e32 v30, v32
	v_mov_b32_e32 v31, v32
	v_mov_b32_e32 v142, 0
	s_branch .LBB0_508
.LBB0_507:
	s_waitcnt lgkmcnt(5)
	v_mfma_f32_32x32x16_bf16 v[32:47], v[222:225], v[160:163], v[32:47]
	ds_read_b128 v[246:249], v192 offset:27680
	v_exp_f32_e32 v168, v96
	v_exp_f32_e32 v169, v97
	s_and_b32 s16, s15, 64
	s_mulk_i32 s16, 0x90
	v_add_f32_e32 v193, v168, v193
	v_add_f32_e32 v142, v169, v142
	v_add_u32_e32 v170, s16, v208
	s_waitcnt lgkmcnt(5)
	v_mfma_f32_32x32x16_bf16 v[64:79], v[226:229], v[160:163], v[64:79]
	ds_read_b128 v[250:253], v192 offset:32288
	v_exp_f32_e32 v164, v98
	v_exp_f32_e32 v165, v99
	s_add_i32 s93, s93, 1
	s_and_b32 s16, s93, 1
	v_add_f32_e32 v193, v164, v193
	v_add_f32_e32 v142, v165, v142
	s_mul_i32 s17, s16, 0x4800
	s_waitcnt lgkmcnt(5)
	v_mfma_f32_32x32x16_bf16 v[48:63], v[230:233], v[160:163], v[48:63]
	ds_read_b128 v[222:225], v192 offset:18496
	v_exp_f32_e32 v141, v100
	v_exp_f32_e32 v101, v101
	s_mulk_i32 s16, 0x2400
	s_add_i32 s15, s15, 64
	s_add_u32 s6, s6, 0x80
	s_addc_u32 s7, s7, 0
	s_cmp_eq_u32 s14, s93
	v_add_f32_e32 v193, v141, v193
	v_add_f32_e32 v142, v101, v142
	s_waitcnt lgkmcnt(5)
	v_mfma_f32_32x32x16_bf16 v[16:31], v[234:237], v[160:163], v[16:31]
	ds_read_b128 v[226:229], v192 offset:23104
	v_exp_f32_e32 v137, v102
	v_exp_f32_e32 v103, v103
	v_add_f32_e32 v193, v137, v193
	v_add_f32_e32 v142, v103, v142
	v_cvt_pk_bf16_f32 v160, v168, v169
	v_cvt_pk_bf16_f32 v161, v164, v165
	v_cvt_pk_bf16_f32 v162, v141, v101
	v_cvt_pk_bf16_f32 v163, v137, v103
	s_waitcnt lgkmcnt(5)
	v_mfma_f32_32x32x16_bf16 v[32:47], v[238:241], v[148:151], v[32:47]
	ds_read_b128 v[230:233], v192 offset:27712
	v_exp_f32_e32 v100, v104
	v_exp_f32_e32 v102, v105
	v_add_f32_e32 v193, v100, v193
	v_add_f32_e32 v142, v102, v142
	s_waitcnt lgkmcnt(5)
	v_mfma_f32_32x32x16_bf16 v[64:79], v[242:245], v[148:151], v[64:79]
	ds_read_b128 v[234:237], v192 offset:32320
	v_exp_f32_e32 v105, v106
	v_exp_f32_e32 v106, v107
	v_add_f32_e32 v193, v105, v193
	v_add_f32_e32 v142, v106, v142
	s_waitcnt lgkmcnt(5)
	v_mfma_f32_32x32x16_bf16 v[48:63], v[246:249], v[148:151], v[48:63]
	ds_read_b128 v[238:241], v192 offset:18528
	v_exp_f32_e32 v107, v108
	v_exp_f32_e32 v108, v109
	v_add_f32_e32 v193, v107, v193
	v_add_f32_e32 v142, v108, v142
	s_waitcnt lgkmcnt(5)
	v_mfma_f32_32x32x16_bf16 v[16:31], v[250:253], v[148:151], v[16:31]
	ds_read_b128 v[242:245], v192 offset:23136
	v_exp_f32_e32 v109, v110
	v_exp_f32_e32 v110, v111
	v_add_f32_e32 v193, v109, v193
	v_add_f32_e32 v142, v110, v142
	v_cvt_pk_bf16_f32 v148, v100, v102
	v_cvt_pk_bf16_f32 v149, v105, v106
	v_cvt_pk_bf16_f32 v150, v107, v108
	v_cvt_pk_bf16_f32 v151, v109, v110
	s_waitcnt lgkmcnt(5)
	v_mfma_f32_32x32x16_bf16 v[32:47], v[222:225], v[152:155], v[32:47]
	ds_read_b128 v[246:249], v192 offset:27744
	v_exp_f32_e32 v100, v80
	v_exp_f32_e32 v102, v81
	v_add_f32_e32 v193, v100, v193
	v_add_f32_e32 v142, v102, v142
	s_waitcnt lgkmcnt(5)
	v_mfma_f32_32x32x16_bf16 v[64:79], v[226:229], v[152:155], v[64:79]
	ds_read_b128 v[250:253], v192 offset:32352
	v_exp_f32_e32 v104, v82
	v_exp_f32_e32 v105, v83
	v_add_f32_e32 v193, v104, v193
	v_add_f32_e32 v142, v105, v142
	s_waitcnt lgkmcnt(5)
	v_mfma_f32_32x32x16_bf16 v[48:63], v[230:233], v[152:155], v[48:63]
	ds_read_b128 v[222:225], v170
	v_exp_f32_e32 v84, v84
	v_exp_f32_e32 v85, v85
	v_add_f32_e32 v193, v84, v193
	v_add_f32_e32 v142, v85, v142
	s_waitcnt lgkmcnt(5)
	v_mfma_f32_32x32x16_bf16 v[16:31], v[234:237], v[152:155], v[16:31]
	ds_read_b128 v[226:229], v170 offset:4608
	v_exp_f32_e32 v86, v86
	v_exp_f32_e32 v87, v87
	v_add_f32_e32 v193, v86, v193
	v_add_f32_e32 v142, v87, v142
	v_cvt_pk_bf16_f32 v152, v100, v102
	v_cvt_pk_bf16_f32 v153, v104, v105
	v_cvt_pk_bf16_f32 v154, v84, v85
	v_cvt_pk_bf16_f32 v155, v86, v87
	s_waitcnt lgkmcnt(5)
	v_mfma_f32_32x32x16_bf16 v[32:47], v[238:241], v[156:159], v[32:47]
	ds_read_b128 v[230:233], v170 offset:4640
	v_exp_f32_e32 v164, v88
	v_exp_f32_e32 v140, v89
	v_add_f32_e32 v193, v164, v193
	v_add_f32_e32 v142, v140, v142
	s_waitcnt lgkmcnt(5)
	v_mfma_f32_32x32x16_bf16 v[64:79], v[242:245], v[156:159], v[64:79]
	ds_read_b128 v[234:237], v170 offset:4672
	v_exp_f32_e32 v100, v90
	v_exp_f32_e32 v136, v91
	v_add_f32_e32 v193, v100, v193
	v_add_f32_e32 v142, v136, v142
	s_waitcnt lgkmcnt(5)
	v_mfma_f32_32x32x16_bf16 v[48:63], v[246:249], v[156:159], v[48:63]
	ds_read_b128 v[238:241], v170 offset:4704
	v_exp_f32_e32 v102, v92
	v_exp_f32_e32 v143, v93
	v_add_f32_e32 v193, v102, v193
	v_add_f32_e32 v142, v143, v142
	s_waitcnt lgkmcnt(5)
	v_mfma_f32_32x32x16_bf16 v[16:31], v[250:253], v[156:159], v[16:31]
	ds_read_b128 v[242:245], v170 offset:32
	v_exp_f32_e32 v138, v94
	v_exp_f32_e32 v84, v95
	v_add_f32_e32 v193, v138, v193
	v_add_f32_e32 v142, v84, v142
	v_cvt_pk_bf16_f32 v156, v164, v140
	v_cvt_pk_bf16_f32 v157, v100, v136
	v_cvt_pk_bf16_f32 v158, v102, v143
	v_cvt_pk_bf16_f32 v159, v138, v84
	s_waitcnt lgkmcnt(5)
	v_mfma_f32_32x32x16_bf16 v[96:111], v[222:225], v[124:127], 0
	ds_read_b128 v[246:249], v170 offset:64
	s_waitcnt lgkmcnt(5)
	v_mfma_f32_32x32x16_bf16 v[80:95], v[226:229], v[124:127], 0
	ds_read_b128 v[250:253], v170 offset:96
	v_add_u32_e32 v168, s17, v212
	s_waitcnt lgkmcnt(5)
	v_mfma_f32_32x32x16_bf16 v[80:95], v[230:233], v[120:123], v[80:95]
	s_waitcnt lgkmcnt(4)
	v_mfma_f32_32x32x16_bf16 v[80:95], v[234:237], v[116:119], v[80:95]
	s_waitcnt lgkmcnt(3)
	v_mfma_f32_32x32x16_bf16 v[80:95], v[238:241], v[112:115], v[80:95]
	s_waitcnt lgkmcnt(2)
	v_mfma_f32_32x32x16_bf16 v[96:111], v[242:245], v[120:123], v[96:111]
	v_lshl_add_u32 v140, v210, 1, v168
	s_waitcnt vmcnt(0)
	ds_write_b64 v140, v[128:129] offset:18432
	v_lshl_add_u32 v128, v211, 1, v168
	ds_write_b64 v140, v[132:133] offset:27648
	ds_write2st64_b64 v128, v[130:131], v[134:135] offset0:36 offset1:54
	v_add_u32_e32 v128, s16, v213
	ds_write_b128 v128, v[144:147]
	s_waitcnt lgkmcnt(5)
	v_mfma_f32_32x32x16_bf16 v[96:111], v[246:249], v[116:119], v[96:111]
	s_waitcnt lgkmcnt(0)
	s_barrier
	v_mfma_f32_32x32x16_bf16 v[96:111], v[250:253], v[112:115], v[96:111]
	s_cbranch_scc1 .Latt_exit_a
.LBB0_508:
	s_andn2_b32 s16, 0x80, s6
	s_mulk_i32 s16, 0x90
	v_add_u32_e32 v192, s16, v208
	ds_read_b128 v[222:225], v192 offset:18432
	ds_read_b128 v[226:229], v192 offset:23040
	ds_read_b128 v[230:233], v192 offset:27648
	ds_read_b128 v[234:237], v192 offset:32256
	ds_read_b128 v[238:241], v192 offset:18464
	ds_read_b128 v[242:245], v192 offset:23072
	s_add_i32 s16, s93, 3
	s_cmp_lt_u32 s16, s13
	s_cselect_b32 s86, s16, s92
	s_add_u32 s16, s90, s6
	s_addc_u32 s17, s91, s7
	global_load_dwordx4 v[128:131], v184, s[16:17]
	s_add_u32 s16, s0, s6
	s_addc_u32 s17, s1, s7
	global_load_dwordx4 v[132:135], v184, s[16:17]
	s_lshl_b64 s[16:17], s[86:87], 17
	s_add_u32 s16, s84, s16
	s_addc_u32 s17, s85, s17
	global_load_dwordx4 v[144:147], v182, s[16:17]
	s_and_saveexec_b64 vcc, s[4:5]
	s_cbranch_execz .LBB0_510
	v_sub_f32_e32 v111, v111, v15
	v_sub_f32_e32 v110, v110, v14
	v_sub_f32_e32 v109, v109, v13
	v_sub_f32_e32 v108, v108, v12
	v_sub_f32_e32 v107, v107, v11
	v_sub_f32_e32 v106, v106, v10
	v_sub_f32_e32 v105, v105, v9
	v_sub_f32_e32 v104, v104, v8
	v_sub_f32_e32 v103, v103, v7
	v_sub_f32_e32 v102, v102, v6
	v_sub_f32_e32 v101, v101, v5
	v_sub_f32_e32 v100, v100, v4
	v_sub_f32_e32 v99, v99, v3
	v_sub_f32_e32 v98, v98, v2
	v_sub_f32_e32 v97, v97, v1
	v_sub_f32_e32 v96, v96, v0
	v_sub_f32_e32 v95, v95, v15
	v_sub_f32_e32 v94, v94, v14
	v_sub_f32_e32 v93, v93, v13
	v_sub_f32_e32 v92, v92, v12
	v_sub_f32_e32 v91, v91, v11
	v_sub_f32_e32 v90, v90, v10
	v_sub_f32_e32 v89, v89, v9
	v_sub_f32_e32 v88, v88, v8
	v_sub_f32_e32 v87, v87, v7
	v_sub_f32_e32 v86, v86, v6
	v_sub_f32_e32 v85, v85, v5
	v_sub_f32_e32 v84, v84, v4
	v_sub_f32_e32 v83, v83, v3
	v_sub_f32_e32 v82, v82, v2
	v_sub_f32_e32 v81, v81, v1
	v_sub_f32_e32 v80, v80, v0

.Latt_exit_a:
	v_add_f32_e32 v193, v193, v142
	s_branch .LBB0_513

.LBB0_539:
	v_add_f32_e32 v16, 0, v32
	v_add_f32_e32 v16, v33, v16
	v_add_f32_e32 v17, 0, v40
	v_add_f32_e32 v16, v34, v16
	v_add_f32_e32 v17, v41, v17
	v_add_f32_e32 v16, v35, v16
	v_add_f32_e32 v17, v42, v17
	v_add_f32_e32 v16, v36, v16
	v_add_f32_e32 v17, v43, v17
	v_add_f32_e32 v16, v37, v16
	v_add_f32_e32 v17, v44, v17
	v_add_f32_e32 v16, v38, v16
	v_add_f32_e32 v17, v45, v17
	v_add_f32_e32 v16, v39, v16
	v_add_f32_e32 v17, v46, v17
	v_add_f32_e32 v16, 0, v16
	v_add_f32_e32 v17, v47, v17
	v_add_f32_e32 v18, 0, v48
	v_add_f32_e32 v16, v17, v16
	v_add_f32_e32 v17, 0, v56
	v_add_f32_e32 v18, v49, v18
	v_add_f32_e32 v17, v57, v17
	v_add_f32_e32 v18, v50, v18
	v_add_f32_e32 v17, v58, v17
	v_add_f32_e32 v18, v51, v18
	v_add_f32_e32 v17, v59, v17
	v_add_f32_e32 v18, v52, v18
	v_add_f32_e32 v17, v60, v17
	v_add_f32_e32 v18, v53, v18
	v_add_f32_e32 v17, v61, v17
	v_add_f32_e32 v18, v54, v18
	s_waitcnt vmcnt(0)
	ds_write_b64 v216, v[64:65] offset:18432
	s_waitcnt lgkmcnt(0)
	ds_write_b64 v216, v[68:69] offset:27648
	ds_write2st64_b64 v217, v[66:67], v[70:71] offset0:36 offset1:54
	ds_write_b128 v213, v[144:147]
	v_add_f32_e32 v17, v62, v17
	v_add_f32_e32 v18, v55, v18
	s_waitcnt lgkmcnt(0)
	s_barrier
	v_add_f32_e32 v17, v63, v17
	v_add_f32_e32 v16, v18, v16
	v_mov_b32_e32 v31, 0
	v_cvt_pk_bf16_f32 v160, v32, v33
	v_cvt_pk_bf16_f32 v161, v34, v35
	v_cvt_pk_bf16_f32 v162, v36, v37
	v_cvt_pk_bf16_f32 v163, v38, v39
	v_cvt_pk_bf16_f32 v148, v40, v41
	v_cvt_pk_bf16_f32 v149, v42, v43
	v_cvt_pk_bf16_f32 v150, v44, v45
	v_cvt_pk_bf16_f32 v151, v46, v47
	v_cvt_pk_bf16_f32 v152, v48, v49
	v_cvt_pk_bf16_f32 v153, v50, v51
	v_cvt_pk_bf16_f32 v154, v52, v53
	v_cvt_pk_bf16_f32 v155, v54, v55
	v_add_f32_e32 v193, v17, v16
	v_cvt_pk_bf16_f32 v156, v56, v57
	v_cvt_pk_bf16_f32 v157, v58, v59
	v_cvt_pk_bf16_f32 v158, v60, v61
	v_cvt_pk_bf16_f32 v159, v62, v63
	s_andn2_b64 vcc, exec, s[80:81]
	s_cbranch_vccnz .LBB0_546
	v_mov_b32_e32 v32, 0
	s_mov_b32 s77, 0
	s_movk_i32 s15, 0x80
	s_mov_b64 s[6:7], 0x80
	v_mov_b32_e32 v33, v32
	v_mov_b32_e32 v34, v32
	v_mov_b32_e32 v35, v32
	v_mov_b32_e32 v36, v32
	v_mov_b32_e32 v37, v32
	v_mov_b32_e32 v38, v32
	v_mov_b32_e32 v39, v32
	v_mov_b32_e32 v40, v32
	v_mov_b32_e32 v41, v32
	v_mov_b32_e32 v42, v32
	v_mov_b32_e32 v43, v32
	v_mov_b32_e32 v44, v32
	v_mov_b32_e32 v45, v32
	v_mov_b32_e32 v46, v32
	v_mov_b32_e32 v47, v32
	v_mov_b32_e32 v64, v32
	v_mov_b32_e32 v65, v32
	v_mov_b32_e32 v66, v32
	v_mov_b32_e32 v67, v32
	v_mov_b32_e32 v68, v32
	v_mov_b32_e32 v69, v32
	v_mov_b32_e32 v70, v32
	v_mov_b32_e32 v71, v32
	v_mov_b32_e32 v72, v32
	v_mov_b32_e32 v73, v32
	v_mov_b32_e32 v74, v32
	v_mov_b32_e32 v75, v32
	v_mov_b32_e32 v76, v32
	v_mov_b32_e32 v77, v32
	v_mov_b32_e32 v78, v32
	v_mov_b32_e32 v79, v32
	v_mov_b32_e32 v48, v32
	v_mov_b32_e32 v49, v32
	v_mov_b32_e32 v50, v32
	v_mov_b32_e32 v51, v32
	v_mov_b32_e32 v52, v32
	v_mov_b32_e32 v53, v32
	v_mov_b32_e32 v54, v32
	v_mov_b32_e32 v55, v32
	v_mov_b32_e32 v56, v32
	v_mov_b32_e32 v57, v32
	v_mov_b32_e32 v58, v32
	v_mov_b32_e32 v59, v32
	v_mov_b32_e32 v60, v32
	v_mov_b32_e32 v61, v32
	v_mov_b32_e32 v62, v32
	v_mov_b32_e32 v63, v32
	v_mov_b32_e32 v16, v32
	v_mov_b32_e32 v17, v32
	v_mov_b32_e32 v18, v32
	v_mov_b32_e32 v19, v32
	v_mov_b32_e32 v20, v32
	v_mov_b32_e32 v21, v32
	v_mov_b32_e32 v22, v32
	v_mov_b32_e32 v23, v32
	v_mov_b32_e32 v24, v32
	v_mov_b32_e32 v25, v32
	v_mov_b32_e32 v26, v32
	v_mov_b32_e32 v27, v32
	v_mov_b32_e32 v28, v32
	v_mov_b32_e32 v29, v32
	v_mov_b32_e32 v30, v32
	v_mov_b32_e32 v31, v32
	v_mov_b32_e32 v142, 0
	s_branch .LBB0_542
.LBB0_541:
	s_waitcnt lgkmcnt(5)
	v_mfma_f32_32x32x16_bf16 v[32:47], v[222:225], v[160:163], v[32:47]
	ds_read_b128 v[246:249], v192 offset:27680
	v_exp_f32_e32 v168, v96
	v_exp_f32_e32 v169, v97
	s_and_b32 s16, s15, 64
	s_mulk_i32 s16, 0x90
	v_add_f32_e32 v193, v168, v193
	v_add_f32_e32 v142, v169, v142
	v_add_u32_e32 v170, s16, v208
	s_waitcnt lgkmcnt(5)
	v_mfma_f32_32x32x16_bf16 v[64:79], v[226:229], v[160:163], v[64:79]
	ds_read_b128 v[250:253], v192 offset:32288
	v_exp_f32_e32 v164, v98
	v_exp_f32_e32 v165, v99
	s_add_i32 s77, s77, 1
	s_and_b32 s16, s77, 1
	v_add_f32_e32 v193, v164, v193
	v_add_f32_e32 v142, v165, v142
	s_mul_i32 s17, s16, 0x4800
	s_waitcnt lgkmcnt(5)
	v_mfma_f32_32x32x16_bf16 v[48:63], v[230:233], v[160:163], v[48:63]
	ds_read_b128 v[222:225], v192 offset:18496
	v_exp_f32_e32 v141, v100
	v_exp_f32_e32 v101, v101
	s_mulk_i32 s16, 0x2400
	s_add_i32 s15, s15, 64
	s_add_u32 s6, s6, 0x80
	s_addc_u32 s7, s7, 0
	s_cmp_eq_u32 s14, s77
	v_add_f32_e32 v193, v141, v193
	v_add_f32_e32 v142, v101, v142
	s_waitcnt lgkmcnt(5)
	v_mfma_f32_32x32x16_bf16 v[16:31], v[234:237], v[160:163], v[16:31]
	ds_read_b128 v[226:229], v192 offset:23104
	v_exp_f32_e32 v137, v102
	v_exp_f32_e32 v103, v103
	v_add_f32_e32 v193, v137, v193
	v_add_f32_e32 v142, v103, v142
	v_cvt_pk_bf16_f32 v160, v168, v169
	v_cvt_pk_bf16_f32 v161, v164, v165
	v_cvt_pk_bf16_f32 v162, v141, v101
	v_cvt_pk_bf16_f32 v163, v137, v103
	s_waitcnt lgkmcnt(5)
	v_mfma_f32_32x32x16_bf16 v[32:47], v[238:241], v[148:151], v[32:47]
	ds_read_b128 v[230:233], v192 offset:27712
	v_exp_f32_e32 v100, v104
	v_exp_f32_e32 v102, v105
	v_add_f32_e32 v193, v100, v193
	v_add_f32_e32 v142, v102, v142
	s_waitcnt lgkmcnt(5)
	v_mfma_f32_32x32x16_bf16 v[64:79], v[242:245], v[148:151], v[64:79]
	ds_read_b128 v[234:237], v192 offset:32320
	v_exp_f32_e32 v105, v106
	v_exp_f32_e32 v106, v107
	v_add_f32_e32 v193, v105, v193
	v_add_f32_e32 v142, v106, v142
	s_waitcnt lgkmcnt(5)
	v_mfma_f32_32x32x16_bf16 v[48:63], v[246:249], v[148:151], v[48:63]
	ds_read_b128 v[238:241], v192 offset:18528
	v_exp_f32_e32 v107, v108
	v_exp_f32_e32 v108, v109
	v_add_f32_e32 v193, v107, v193
	v_add_f32_e32 v142, v108, v142
	s_waitcnt lgkmcnt(5)
	v_mfma_f32_32x32x16_bf16 v[16:31], v[250:253], v[148:151], v[16:31]
	ds_read_b128 v[242:245], v192 offset:23136
	v_exp_f32_e32 v109, v110
	v_exp_f32_e32 v110, v111
	v_add_f32_e32 v193, v109, v193
	v_add_f32_e32 v142, v110, v142
	v_cvt_pk_bf16_f32 v148, v100, v102
	v_cvt_pk_bf16_f32 v149, v105, v106
	v_cvt_pk_bf16_f32 v150, v107, v108
	v_cvt_pk_bf16_f32 v151, v109, v110
	s_waitcnt lgkmcnt(5)
	v_mfma_f32_32x32x16_bf16 v[32:47], v[222:225], v[152:155], v[32:47]
	ds_read_b128 v[246:249], v192 offset:27744
	v_exp_f32_e32 v100, v80
	v_exp_f32_e32 v102, v81
	v_add_f32_e32 v193, v100, v193
	v_add_f32_e32 v142, v102, v142
	s_waitcnt lgkmcnt(5)
	v_mfma_f32_32x32x16_bf16 v[64:79], v[226:229], v[152:155], v[64:79]
	ds_read_b128 v[250:253], v192 offset:32352
	v_exp_f32_e32 v104, v82
	v_exp_f32_e32 v105, v83
	v_add_f32_e32 v193, v104, v193
	v_add_f32_e32 v142, v105, v142
	s_waitcnt lgkmcnt(5)
	v_mfma_f32_32x32x16_bf16 v[48:63], v[230:233], v[152:155], v[48:63]
	ds_read_b128 v[222:225], v170
	v_exp_f32_e32 v84, v84
	v_exp_f32_e32 v85, v85
	v_add_f32_e32 v193, v84, v193
	v_add_f32_e32 v142, v85, v142
	s_waitcnt lgkmcnt(5)
	v_mfma_f32_32x32x16_bf16 v[16:31], v[234:237], v[152:155], v[16:31]
	ds_read_b128 v[226:229], v170 offset:4608
	v_exp_f32_e32 v86, v86
	v_exp_f32_e32 v87, v87
	v_add_f32_e32 v193, v86, v193
	v_add_f32_e32 v142, v87, v142
	v_cvt_pk_bf16_f32 v152, v100, v102
	v_cvt_pk_bf16_f32 v153, v104, v105
	v_cvt_pk_bf16_f32 v154, v84, v85
	v_cvt_pk_bf16_f32 v155, v86, v87
	s_waitcnt lgkmcnt(5)
	v_mfma_f32_32x32x16_bf16 v[32:47], v[238:241], v[156:159], v[32:47]
	ds_read_b128 v[230:233], v170 offset:4640
	v_exp_f32_e32 v164, v88
	v_exp_f32_e32 v140, v89
	v_add_f32_e32 v193, v164, v193
	v_add_f32_e32 v142, v140, v142
	s_waitcnt lgkmcnt(5)
	v_mfma_f32_32x32x16_bf16 v[64:79], v[242:245], v[156:159], v[64:79]
	ds_read_b128 v[234:237], v170 offset:4672
	v_exp_f32_e32 v100, v90
	v_exp_f32_e32 v136, v91
	v_add_f32_e32 v193, v100, v193
	v_add_f32_e32 v142, v136, v142
	s_waitcnt lgkmcnt(5)
	v_mfma_f32_32x32x16_bf16 v[48:63], v[246:249], v[156:159], v[48:63]
	ds_read_b128 v[238:241], v170 offset:4704
	v_exp_f32_e32 v102, v92
	v_exp_f32_e32 v143, v93
	v_add_f32_e32 v193, v102, v193
	v_add_f32_e32 v142, v143, v142
	s_waitcnt lgkmcnt(5)
	v_mfma_f32_32x32x16_bf16 v[16:31], v[250:253], v[156:159], v[16:31]
	ds_read_b128 v[242:245], v170 offset:32
	v_exp_f32_e32 v138, v94
	v_exp_f32_e32 v84, v95
	v_add_f32_e32 v193, v138, v193
	v_add_f32_e32 v142, v84, v142
	v_cvt_pk_bf16_f32 v156, v164, v140
	v_cvt_pk_bf16_f32 v157, v100, v136
	v_cvt_pk_bf16_f32 v158, v102, v143
	v_cvt_pk_bf16_f32 v159, v138, v84
	s_waitcnt lgkmcnt(5)
	v_mfma_f32_32x32x16_bf16 v[96:111], v[222:225], v[124:127], 0
	ds_read_b128 v[246:249], v170 offset:64
	s_waitcnt lgkmcnt(5)
	v_mfma_f32_32x32x16_bf16 v[80:95], v[226:229], v[124:127], 0
	ds_read_b128 v[250:253], v170 offset:96
	v_add_u32_e32 v168, s17, v212
	s_waitcnt lgkmcnt(5)
	v_mfma_f32_32x32x16_bf16 v[80:95], v[230:233], v[120:123], v[80:95]
	s_waitcnt lgkmcnt(4)
	v_mfma_f32_32x32x16_bf16 v[80:95], v[234:237], v[116:119], v[80:95]
	s_waitcnt lgkmcnt(3)
	v_mfma_f32_32x32x16_bf16 v[80:95], v[238:241], v[112:115], v[80:95]
	s_waitcnt lgkmcnt(2)
	v_mfma_f32_32x32x16_bf16 v[96:111], v[242:245], v[120:123], v[96:111]
	v_lshl_add_u32 v140, v210, 1, v168
	s_waitcnt vmcnt(0)
	ds_write_b64 v140, v[128:129] offset:18432
	v_lshl_add_u32 v128, v211, 1, v168
	ds_write_b64 v140, v[132:133] offset:27648
	ds_write2st64_b64 v128, v[130:131], v[134:135] offset0:36 offset1:54
	v_add_u32_e32 v128, s16, v213
	ds_write_b128 v128, v[144:147]
	s_waitcnt lgkmcnt(5)
	v_mfma_f32_32x32x16_bf16 v[96:111], v[246:249], v[116:119], v[96:111]
	s_waitcnt lgkmcnt(0)
	s_barrier
	v_mfma_f32_32x32x16_bf16 v[96:111], v[250:253], v[112:115], v[96:111]
	s_cbranch_scc1 .Latt_exit_b
.LBB0_542:
	s_andn2_b32 s16, 0x80, s6
	s_mulk_i32 s16, 0x90
	v_add_u32_e32 v192, s16, v208
	ds_read_b128 v[222:225], v192 offset:18432
	ds_read_b128 v[226:229], v192 offset:23040
	ds_read_b128 v[230:233], v192 offset:27648
	ds_read_b128 v[234:237], v192 offset:32256
	ds_read_b128 v[238:241], v192 offset:18464
	ds_read_b128 v[242:245], v192 offset:23072
	s_add_i32 s16, s77, 3
	s_cmp_lt_u32 s16, s13
	s_cselect_b32 s86, s16, s76
	s_add_u32 s16, s90, s6
	s_addc_u32 s17, s91, s7
	global_load_dwordx4 v[128:131], v184, s[16:17]
	s_add_u32 s16, s0, s6
	s_addc_u32 s17, s1, s7
	global_load_dwordx4 v[132:135], v184, s[16:17]
	s_lshl_b64 s[16:17], s[86:87], 17
	s_add_u32 s16, s96, s16
	s_addc_u32 s17, s97, s17
	global_load_dwordx4 v[144:147], v182, s[16:17]
	s_and_saveexec_b64 vcc, s[4:5]
	s_cbranch_execz .LBB0_544
	v_sub_f32_e32 v111, v111, v15
	v_sub_f32_e32 v110, v110, v14
	v_sub_f32_e32 v109, v109, v13
	v_sub_f32_e32 v108, v108, v12
	v_sub_f32_e32 v107, v107, v11
	v_sub_f32_e32 v106, v106, v10
	v_sub_f32_e32 v105, v105, v9
	v_sub_f32_e32 v104, v104, v8
	v_sub_f32_e32 v103, v103, v7
	v_sub_f32_e32 v102, v102, v6
	v_sub_f32_e32 v101, v101, v5
	v_sub_f32_e32 v100, v100, v4
	v_sub_f32_e32 v99, v99, v3
	v_sub_f32_e32 v98, v98, v2
	v_sub_f32_e32 v97, v97, v1
	v_sub_f32_e32 v96, v96, v0
	v_sub_f32_e32 v95, v95, v15
	v_sub_f32_e32 v94, v94, v14
	v_sub_f32_e32 v93, v93, v13
	v_sub_f32_e32 v92, v92, v12
	v_sub_f32_e32 v91, v91, v11
	v_sub_f32_e32 v90, v90, v10
	v_sub_f32_e32 v89, v89, v9
	v_sub_f32_e32 v88, v88, v8
	v_sub_f32_e32 v87, v87, v7
	v_sub_f32_e32 v86, v86, v6
	v_sub_f32_e32 v85, v85, v5
	v_sub_f32_e32 v84, v84, v4
	v_sub_f32_e32 v83, v83, v3
	v_sub_f32_e32 v82, v82, v2
	v_sub_f32_e32 v81, v81, v1
	v_sub_f32_e32 v80, v80, v0
